# P1 norm gains hoisted out of row loop (no per-store vmcnt(0)); lru_local conv-history loads no longer drain prefetch batch; lru_out global->LDS copy chain de-serialised
# speedup vs baseline: 1.0168x; 1.0015x over previous
.LBB0_149:
	s_or_b64 exec, exec, s[6:7]
	s_waitcnt vmcnt(0)
	v_ashrrev_i32_e32 v2, 6, v4
	v_readlane_b32 s0, v253, 2
	s_waitcnt lgkmcnt(0)
	s_barrier
	v_add_u32_e32 v180, s0, v2
	v_cmp_gt_i32_e32 vcc, s2, v180
	s_and_saveexec_b64 s[10:11], vcc
	s_cbranch_execz .LBB0_156
	v_ashrrev_i32_e32 v181, 31, v180
	v_and_b32_e32 v134, 63, v4
	v_lshlrev_b64 v[2:3], 12, v[180:181]
	v_lshl_add_u64 v[2:3], v[212:213], 0, v[2:3]
	v_lshlrev_b32_e32 v166, 4, v134
	v_lshl_add_u64 v[2:3], v[2:3], 0, v[166:167]
	global_load_dwordx4 v[160:163], v[2:3], off
	global_load_dwordx4 v[156:159], v[2:3], off offset:1024
	global_load_dwordx4 v[152:155], v[2:3], off offset:2048
	global_load_dwordx4 v[148:151], v[2:3], off offset:3072
	s_mov_b64 s[6:7], 0x7300000
	s_lshl_b32 s96, s83, 10
	v_lshl_add_u64 v[164:165], v[132:133], 0, s[6:7]
	s_lshl_b64 s[6:7], s[96:97], 2
	v_lshl_add_u64 v[0:1], v[0:1], 0, s[6:7]
	v_lshl_add_u32 v128, v134, 7, 0
	v_lshl_add_u64 v[178:179], v[0:1], 0, v[166:167]
	ds_read_b128 v[0:3], v128
	ds_read_b128 v[4:7], v128 offset:16
	ds_read_b128 v[8:11], v128 offset:32
	ds_read_b128 v[12:15], v128 offset:48
	ds_read_b128 v[16:19], v128 offset:64
	ds_read_b128 v[20:23], v128 offset:80
	ds_read_b128 v[24:27], v128 offset:96
	ds_read_b128 v[28:31], v128 offset:112
	ds_read_b128 v[32:35], v128 offset:8192
	ds_read_b128 v[36:39], v128 offset:8208
	ds_read_b128 v[40:43], v128 offset:8224
	ds_read_b128 v[44:47], v128 offset:8240
	ds_read_b128 v[48:51], v128 offset:8256
	ds_read_b128 v[52:55], v128 offset:8272
	ds_read_b128 v[56:59], v128 offset:8288
	ds_read_b128 v[60:63], v128 offset:8304
	ds_read_b128 v[64:67], v128 offset:16384
	ds_read_b128 v[68:71], v128 offset:16400
	ds_read_b128 v[72:75], v128 offset:16416
	ds_read_b128 v[76:79], v128 offset:16432
	ds_read_b128 v[84:87], v128 offset:16448
	ds_read_b128 v[88:91], v128 offset:16464
	ds_read_b128 v[92:95], v128 offset:16480
	ds_read_b128 v[96:99], v128 offset:16496
	ds_read_b128 v[100:103], v128 offset:24576
	ds_read_b128 v[104:107], v128 offset:24592
	ds_read_b128 v[108:111], v128 offset:24608
	ds_read_b128 v[112:115], v128 offset:24624
	ds_read_b128 v[116:119], v128 offset:24640
	ds_read_b128 v[120:123], v128 offset:24656
	ds_read_b128 v[124:127], v128 offset:24672
	ds_read_b128 v[128:131], v128 offset:24688
	v_lshl_add_u64 v[176:177], v[212:213], 0, v[166:167]
	v_lshlrev_b32_e32 v166, 3, v134
	v_lshl_add_u64 v[132:133], v[132:133], 0, v[166:167]
	s_mov_b64 s[6:7], 0x5300000
	v_cmp_eq_u32_e32 vcc, 0, v134
	v_lshl_add_u64 v[182:183], v[132:133], 0, s[6:7]
	s_mov_b64 s[12:13], 0
	global_load_dwordx4 v[196:199], v[178:179], off
	global_load_dwordx4 v[200:203], v[178:179], off offset:1024
	global_load_dwordx4 v[204:207], v[178:179], off offset:2048
	global_load_dwordx4 v[224:227], v[178:179], off offset:3072
	s_waitcnt vmcnt(0)
	s_branch .LBB0_152

.LBB0_152:
	v_add_u32_e32 v184, s75, v180
	s_movk_i32 s5, 0x3fff
	v_cmp_gt_i32_e64 s[8:9], s2, v184
	v_cmp_lt_i32_e64 s[6:7], s5, v184
	v_mov_b32_e32 v132, v160
	v_mov_b32_e32 v133, v161
	v_mov_b32_e32 v134, v162
	v_mov_b32_e32 v135, v163
	v_mov_b32_e32 v136, v156
	v_mov_b32_e32 v137, v157
	v_mov_b32_e32 v138, v158
	v_mov_b32_e32 v139, v159
	v_mov_b32_e32 v140, v152
	v_mov_b32_e32 v141, v153
	v_mov_b32_e32 v142, v154
	v_mov_b32_e32 v143, v155
	v_mov_b32_e32 v144, v148
	v_mov_b32_e32 v145, v149
	v_mov_b32_e32 v146, v150
	v_mov_b32_e32 v147, v151
	s_and_saveexec_b64 s[14:15], s[8:9]
	s_cbranch_execz .LBB0_154
	v_ashrrev_i32_e32 v185, 31, v184
	v_lshlrev_b64 v[132:133], 12, v[184:185]
	v_lshl_add_u64 v[144:145], v[176:177], 0, v[132:133]
	global_load_dwordx4 v[132:135], v[144:145], off
	global_load_dwordx4 v[136:139], v[144:145], off offset:1024
	global_load_dwordx4 v[140:143], v[144:145], off offset:2048
	s_nop 0
	global_load_dwordx4 v[144:147], v[144:145], off offset:3072
.LBB0_154:
	s_or_b64 exec, exec, s[14:15]
	v_mul_f32_e32 v166, v161, v161
	v_mul_f32_e32 v169, v157, v157
	v_mul_f32_e32 v170, v153, v153
	v_fmac_f32_e32 v166, v160, v160
	v_fmac_f32_e32 v169, v156, v156
	v_mul_f32_e32 v171, v149, v149
	v_fmac_f32_e32 v170, v152, v152
	v_fmac_f32_e32 v166, v162, v162
	v_fmac_f32_e32 v169, v158, v158
	v_fmac_f32_e32 v171, v148, v148
	v_fmac_f32_e32 v170, v154, v154
	v_fmac_f32_e32 v166, v163, v163
	v_fmac_f32_e32 v169, v159, v159
	v_fmac_f32_e32 v171, v150, v150
	v_fmac_f32_e32 v170, v155, v155
	v_add_f32_e32 v166, v166, v169
	v_fmac_f32_e32 v171, v151, v151
	v_add_f32_e32 v166, v170, v166
	v_add_f32_e32 v166, v171, v166
	v_mov_b32_e32 v169, 0x358637bd
	v_ashrrev_i32_e32 v181, 31, v180
	v_add_f32_dpp v166, v166, v166 row_ror:8 row_mask:0xf bank_mask:0xf bound_ctrl:1
	s_nop 1
	v_add_f32_dpp v166, v166, v166 row_ror:4 row_mask:0xf bank_mask:0xf bound_ctrl:1
	s_nop 1
	v_add_f32_dpp v166, v166, v166 row_ror:2 row_mask:0xf bank_mask:0xf bound_ctrl:1
	s_nop 1
	v_add_f32_dpp v166, v166, v166 row_ror:1 row_mask:0xf bank_mask:0xf bound_ctrl:1
	s_nop 0
	v_readlane_b32 s5, v166, 16
	v_readlane_b32 s14, v166, 48
	v_readlane_b32 s8, v166, 0
	v_readlane_b32 s9, v166, 32
	v_mov_b32_e32 v186, s5
	v_mov_b32_e32 v187, s14
	v_pk_add_f32 v[186:187], s[8:9], v[186:187]
	s_nop 0
	v_add_f32_e32 v166, v186, v187
	v_fmamk_f32 v166, v166, 0x3a800000, v169
	v_mul_f32_e32 v169, 0x4b800000, v166
	v_cmp_gt_f32_e64 s[8:9], s58, v166
	v_lshlrev_b64 v[186:187], 11, v[180:181]
	v_lshl_add_u64 v[186:187], v[182:183], 0, v[186:187]
	v_cndmask_b32_e64 v166, v166, v169, s[8:9]
	v_rsq_f32_e32 v166, v166
	s_nop 0
	v_mul_f32_e32 v169, 0x45800000, v166
	v_cndmask_b32_e64 v166, v166, v169, s[8:9]
	v_pk_mul_f32 v[160:161], v[160:161], v[166:167] op_sel_hi:[1,0]
	v_pk_mul_f32 v[162:163], v[162:163], v[166:167] op_sel_hi:[1,0]
	v_pk_mul_f32 v[156:157], v[156:157], v[166:167] op_sel_hi:[1,0]
	v_pk_mul_f32 v[158:159], v[158:159], v[166:167] op_sel_hi:[1,0]
	v_pk_mul_f32 v[152:153], v[152:153], v[166:167] op_sel_hi:[1,0]
	v_pk_mul_f32 v[154:155], v[154:155], v[166:167] op_sel_hi:[1,0]
	v_pk_mul_f32 v[192:193], v[148:149], v[166:167] op_sel_hi:[1,0]
	v_pk_mul_f32 v[194:195], v[150:151], v[166:167] op_sel_hi:[1,0]
	v_pk_mul_f32 v[188:189], v[196:197], v[160:161]
	v_pk_mul_f32 v[190:191], v[198:199], v[162:163]
	v_cvt_pk_bf16_f32 v160, v188, v189
	v_cvt_pk_bf16_f32 v161, v190, v191
	global_store_dwordx2 v[186:187], v[160:161], off
	s_waitcnt lgkmcnt(14)
	v_fma_f32 v166, v0, v188, 0
	v_fma_f32 v169, v1, v188, 0
	v_fma_f32 v170, v2, v188, 0
	v_fma_f32 v171, v3, v188, 0
	v_fma_f32 v172, v4, v188, 0
	v_fma_f32 v173, v5, v188, 0
	v_fma_f32 v185, v6, v188, 0
	v_fma_f32 v188, v7, v188, 0
	v_fmac_f32_e32 v166, v8, v189
	v_fmac_f32_e32 v169, v9, v189
	v_fmac_f32_e32 v170, v10, v189
	v_fmac_f32_e32 v171, v11, v189
	v_fmac_f32_e32 v172, v12, v189
	v_fmac_f32_e32 v173, v13, v189
	v_fmac_f32_e32 v185, v14, v189
	v_fmac_f32_e32 v188, v15, v189
	v_fmac_f32_e32 v166, v16, v190
	v_fmac_f32_e32 v169, v17, v190
	v_fmac_f32_e32 v170, v18, v190
	v_fmac_f32_e32 v171, v19, v190
	v_fmac_f32_e32 v172, v20, v190
	v_fmac_f32_e32 v173, v21, v190
	v_fmac_f32_e32 v185, v22, v190
	v_fmac_f32_e32 v188, v23, v190
	v_fmac_f32_e32 v166, v24, v191
	v_fmac_f32_e32 v169, v25, v191
	v_fmac_f32_e32 v170, v26, v191
	v_fmac_f32_e32 v171, v27, v191
	v_fmac_f32_e32 v172, v28, v191
	v_fmac_f32_e32 v173, v29, v191
	v_fmac_f32_e32 v185, v30, v191
	v_fmac_f32_e32 v188, v31, v191
	v_pk_mul_f32 v[160:161], v[156:157], v[200:201]
	v_pk_mul_f32 v[162:163], v[158:159], v[202:203]
	v_cvt_pk_bf16_f32 v156, v160, v161
	v_cvt_pk_bf16_f32 v157, v162, v163
	global_store_dwordx2 v[186:187], v[156:157], off offset:512
	v_fmac_f32_e32 v166, v160, v32
	v_fmac_f32_e32 v169, v160, v33
	v_fmac_f32_e32 v170, v160, v34
	v_fmac_f32_e32 v171, v160, v35
	v_fmac_f32_e32 v172, v160, v36
	v_fmac_f32_e32 v173, v160, v37
	v_fmac_f32_e32 v185, v160, v38
	v_fmac_f32_e32 v188, v160, v39
	v_fmac_f32_e32 v166, v161, v40
	v_fmac_f32_e32 v169, v161, v41
	v_fmac_f32_e32 v170, v161, v42
	v_fmac_f32_e32 v171, v161, v43
	v_fmac_f32_e32 v172, v161, v44
	v_fmac_f32_e32 v173, v161, v45
	v_fmac_f32_e32 v185, v161, v46
	v_fmac_f32_e32 v188, v161, v47
	v_fmac_f32_e32 v166, v162, v48
	v_fmac_f32_e32 v169, v162, v49
	v_fmac_f32_e32 v170, v162, v50
	v_fmac_f32_e32 v171, v162, v51
	v_fmac_f32_e32 v172, v162, v52
	v_fmac_f32_e32 v173, v162, v53
	v_fmac_f32_e32 v185, v162, v54
	v_fmac_f32_e32 v188, v162, v55
	v_fmac_f32_e32 v166, v163, v56
	v_fmac_f32_e32 v169, v163, v57
	v_fmac_f32_e32 v170, v163, v58
	v_fmac_f32_e32 v171, v163, v59
	v_fmac_f32_e32 v172, v163, v60
	v_fmac_f32_e32 v173, v163, v61
	v_fmac_f32_e32 v185, v163, v62
	v_fmac_f32_e32 v188, v163, v63
	v_pk_mul_f32 v[152:153], v[152:153], v[204:205]
	v_pk_mul_f32 v[154:155], v[154:155], v[206:207]
	v_cvt_pk_bf16_f32 v148, v152, v153
	v_cvt_pk_bf16_f32 v149, v154, v155
	global_store_dwordx2 v[186:187], v[148:149], off offset:1024
	v_fmac_f32_e32 v166, v152, v64
	v_fmac_f32_e32 v169, v152, v65
	v_fmac_f32_e32 v170, v152, v66
	v_fmac_f32_e32 v171, v152, v67
	v_fmac_f32_e32 v172, v152, v68
	v_fmac_f32_e32 v173, v152, v69
	v_fmac_f32_e32 v185, v152, v70
	v_fmac_f32_e32 v188, v152, v71
	s_waitcnt lgkmcnt(13)
	v_fmac_f32_e32 v166, v153, v72
	v_fmac_f32_e32 v169, v153, v73
	v_fmac_f32_e32 v170, v153, v74
	v_fmac_f32_e32 v171, v153, v75
	s_waitcnt lgkmcnt(12)
	v_fmac_f32_e32 v172, v153, v76
	v_fmac_f32_e32 v173, v153, v77
	v_fmac_f32_e32 v185, v153, v78
	v_fmac_f32_e32 v188, v153, v79
	s_waitcnt lgkmcnt(11)
	v_fmac_f32_e32 v166, v154, v84
	v_fmac_f32_e32 v169, v154, v85
	v_fmac_f32_e32 v170, v154, v86
	v_fmac_f32_e32 v171, v154, v87
	s_waitcnt lgkmcnt(10)
	v_fmac_f32_e32 v172, v154, v88
	v_fmac_f32_e32 v173, v154, v89
	v_fmac_f32_e32 v185, v154, v90
	v_fmac_f32_e32 v188, v154, v91
	s_waitcnt lgkmcnt(9)
	v_fmac_f32_e32 v166, v155, v92
	v_fmac_f32_e32 v169, v155, v93
	v_fmac_f32_e32 v170, v155, v94
	v_fmac_f32_e32 v171, v155, v95
	s_waitcnt lgkmcnt(8)
	v_fmac_f32_e32 v172, v155, v96
	v_fmac_f32_e32 v173, v155, v97
	v_fmac_f32_e32 v185, v155, v98
	v_fmac_f32_e32 v188, v155, v99
	v_pk_mul_f32 v[148:149], v[192:193], v[224:225]
	s_waitcnt lgkmcnt(7)
	v_fmac_f32_e32 v166, v148, v100
	v_fmac_f32_e32 v169, v148, v101
	v_fmac_f32_e32 v170, v148, v102
	v_fmac_f32_e32 v171, v148, v103
	s_waitcnt lgkmcnt(6)
	v_fmac_f32_e32 v172, v148, v104
	v_fmac_f32_e32 v173, v148, v105
	v_fmac_f32_e32 v185, v148, v106
	v_fmac_f32_e32 v188, v148, v107
	v_pk_mul_f32 v[150:151], v[194:195], v[226:227]
	s_waitcnt lgkmcnt(5)
	v_fmac_f32_e32 v166, v149, v108
	v_fmac_f32_e32 v169, v149, v109
	v_fmac_f32_e32 v170, v149, v110
	v_fmac_f32_e32 v171, v149, v111
	s_waitcnt lgkmcnt(4)
	v_fmac_f32_e32 v172, v149, v112
	v_fmac_f32_e32 v173, v149, v113
	v_fmac_f32_e32 v185, v149, v114
	v_fmac_f32_e32 v188, v149, v115
	s_waitcnt lgkmcnt(3)
	v_fmac_f32_e32 v166, v150, v116
	v_fmac_f32_e32 v169, v150, v117
	v_fmac_f32_e32 v170, v150, v118
	v_fmac_f32_e32 v171, v150, v119
	s_waitcnt lgkmcnt(2)
	v_fmac_f32_e32 v172, v150, v120
	v_fmac_f32_e32 v173, v150, v121
	v_fmac_f32_e32 v185, v150, v122
	v_fmac_f32_e32 v188, v150, v123
	v_cvt_pk_bf16_f32 v152, v148, v149
	v_cvt_pk_bf16_f32 v153, v150, v151
	s_waitcnt lgkmcnt(1)
	v_fmac_f32_e32 v166, v151, v124
	v_fmac_f32_e32 v169, v151, v125
	v_fmac_f32_e32 v170, v151, v126
	v_fmac_f32_e32 v171, v151, v127
	s_waitcnt lgkmcnt(0)
	v_fmac_f32_e32 v172, v151, v128
	v_fmac_f32_e32 v173, v151, v129
	v_fmac_f32_e32 v185, v151, v130
	v_fmac_f32_e32 v188, v151, v131
	global_store_dwordx2 v[186:187], v[152:153], off offset:1536
	v_add_f32_dpp v148, v166, v166 row_ror:8 row_mask:0xf bank_mask:0xf bound_ctrl:1
	v_add_f32_dpp v149, v169, v169 row_ror:8 row_mask:0xf bank_mask:0xf bound_ctrl:1
	v_add_f32_dpp v150, v170, v170 row_ror:8 row_mask:0xf bank_mask:0xf bound_ctrl:1
	v_add_f32_dpp v151, v171, v171 row_ror:8 row_mask:0xf bank_mask:0xf bound_ctrl:1
	v_add_f32_dpp v152, v172, v172 row_ror:8 row_mask:0xf bank_mask:0xf bound_ctrl:1
	v_add_f32_dpp v153, v173, v173 row_ror:8 row_mask:0xf bank_mask:0xf bound_ctrl:1
	v_add_f32_dpp v154, v185, v185 row_ror:8 row_mask:0xf bank_mask:0xf bound_ctrl:1
	v_add_f32_dpp v155, v188, v188 row_ror:8 row_mask:0xf bank_mask:0xf bound_ctrl:1
	v_add_f32_dpp v148, v148, v148 row_ror:4 row_mask:0xf bank_mask:0xf bound_ctrl:1
	v_add_f32_dpp v149, v149, v149 row_ror:4 row_mask:0xf bank_mask:0xf bound_ctrl:1
	v_add_f32_dpp v150, v150, v150 row_ror:4 row_mask:0xf bank_mask:0xf bound_ctrl:1
	v_add_f32_dpp v151, v151, v151 row_ror:4 row_mask:0xf bank_mask:0xf bound_ctrl:1
	v_add_f32_dpp v152, v152, v152 row_ror:4 row_mask:0xf bank_mask:0xf bound_ctrl:1
	v_add_f32_dpp v153, v153, v153 row_ror:4 row_mask:0xf bank_mask:0xf bound_ctrl:1
	v_add_f32_dpp v154, v154, v154 row_ror:4 row_mask:0xf bank_mask:0xf bound_ctrl:1
	v_add_f32_dpp v155, v155, v155 row_ror:4 row_mask:0xf bank_mask:0xf bound_ctrl:1
	v_add_f32_dpp v148, v148, v148 row_ror:2 row_mask:0xf bank_mask:0xf bound_ctrl:1
	v_add_f32_dpp v149, v149, v149 row_ror:2 row_mask:0xf bank_mask:0xf bound_ctrl:1
	v_add_f32_dpp v150, v150, v150 row_ror:2 row_mask:0xf bank_mask:0xf bound_ctrl:1
	v_add_f32_dpp v151, v151, v151 row_ror:2 row_mask:0xf bank_mask:0xf bound_ctrl:1
	v_add_f32_dpp v152, v152, v152 row_ror:2 row_mask:0xf bank_mask:0xf bound_ctrl:1
	v_add_f32_dpp v153, v153, v153 row_ror:2 row_mask:0xf bank_mask:0xf bound_ctrl:1
	v_add_f32_dpp v154, v154, v154 row_ror:2 row_mask:0xf bank_mask:0xf bound_ctrl:1
	v_add_f32_dpp v155, v155, v155 row_ror:2 row_mask:0xf bank_mask:0xf bound_ctrl:1
	v_add_f32_dpp v148, v148, v148 row_ror:1 row_mask:0xf bank_mask:0xf bound_ctrl:1
	v_add_f32_dpp v149, v149, v149 row_ror:1 row_mask:0xf bank_mask:0xf bound_ctrl:1
	v_add_f32_dpp v150, v150, v150 row_ror:1 row_mask:0xf bank_mask:0xf bound_ctrl:1
	v_add_f32_dpp v151, v151, v151 row_ror:1 row_mask:0xf bank_mask:0xf bound_ctrl:1
	v_add_f32_dpp v152, v152, v152 row_ror:1 row_mask:0xf bank_mask:0xf bound_ctrl:1
	v_add_f32_dpp v153, v153, v153 row_ror:1 row_mask:0xf bank_mask:0xf bound_ctrl:1
	v_add_f32_dpp v154, v154, v154 row_ror:1 row_mask:0xf bank_mask:0xf bound_ctrl:1
	v_add_f32_dpp v155, v155, v155 row_ror:1 row_mask:0xf bank_mask:0xf bound_ctrl:1
	v_readlane_b32 s18, v148, 0
	v_readlane_b32 s35, v148, 16
	v_readlane_b32 s8, v148, 32
	v_readlane_b32 s5, v148, 48
	v_readlane_b32 s19, v149, 0
	v_readlane_b32 s37, v149, 16
	v_readlane_b32 s9, v149, 32
	v_readlane_b32 s31, v149, 48
	v_readlane_b32 s20, v150, 0
	v_readlane_b32 s36, v150, 16
	v_readlane_b32 s14, v150, 32
	v_readlane_b32 s30, v150, 48
	v_readlane_b32 s21, v151, 0
	v_readlane_b32 s38, v151, 16
	v_readlane_b32 s15, v151, 32
	v_readlane_b32 s34, v151, 48
	v_readlane_b32 s26, v152, 0
	v_readlane_b32 s43, v152, 16
	v_readlane_b32 s22, v152, 32
	v_readlane_b32 s39, v152, 48
	v_readlane_b32 s27, v153, 0
	v_readlane_b32 s45, v153, 16
	v_readlane_b32 s23, v153, 32
	v_readlane_b32 s41, v153, 48
	v_readlane_b32 s28, v154, 0
	v_readlane_b32 s44, v154, 16
	v_readlane_b32 s24, v154, 32
	v_readlane_b32 s40, v154, 48
	v_readlane_b32 s29, v155, 0
	v_readlane_b32 s46, v155, 16
	v_readlane_b32 s25, v155, 32
	v_readlane_b32 s42, v155, 48
	s_waitcnt vmcnt(4)
	s_and_saveexec_b64 s[16:17], vcc
	s_cbranch_execz .LBB0_151
	v_lshlrev_b64 v[148:149], 5, v[180:181]
	v_lshl_add_u64 v[156:157], v[164:165], 0, v[148:149]
	v_mov_b32_e32 v148, s43
	v_mov_b32_e32 v149, s45
	v_mov_b32_e32 v150, s44
	v_mov_b32_e32 v151, s46
	v_mov_b32_e32 v152, s39
	v_mov_b32_e32 v153, s41
	v_mov_b32_e32 v154, s40
	v_mov_b32_e32 v155, s42
	v_pk_add_f32 v[148:149], s[26:27], v[148:149]
	v_pk_add_f32 v[150:151], s[28:29], v[150:151]
	v_pk_add_f32 v[152:153], s[22:23], v[152:153]
	v_pk_add_f32 v[154:155], s[24:25], v[154:155]
	v_pk_add_f32 v[148:149], v[148:149], v[152:153]
	v_pk_add_f32 v[150:151], v[150:151], v[154:155]
	v_mov_b32_e32 v152, s35
	v_mov_b32_e32 v153, s37
	v_mov_b32_e32 v154, s36
	v_mov_b32_e32 v155, s38
	v_mov_b32_e32 v158, s5
	v_mov_b32_e32 v159, s31
	v_mov_b32_e32 v160, s30
	v_mov_b32_e32 v161, s34
	v_pk_add_f32 v[152:153], s[18:19], v[152:153]
	v_pk_add_f32 v[154:155], s[20:21], v[154:155]
	v_pk_add_f32 v[158:159], s[8:9], v[158:159]
	v_pk_add_f32 v[160:161], s[14:15], v[160:161]
	v_pk_add_f32 v[152:153], v[152:153], v[158:159]
	v_pk_add_f32 v[154:155], v[154:155], v[160:161]
	global_store_dwordx4 v[156:157], v[152:155], off
	global_store_dwordx4 v[156:157], v[148:151], off offset:16
	s_branch .LBB0_151

.LBB0_311:
	s_mov_b64 s[8:9], s[62:63]
	global_load_dwordx2 v[12:13], v167, s[8:9] offset:112
	global_load_dwordx4 v[4:7], v167, s[8:9] offset:96
	global_load_dwordx4 v[8:11], v167, s[8:9] offset:80
	global_load_dwordx4 v[0:3], v167, s[8:9] offset:64
	global_load_dwordx2 v[64:65], v167, s[8:9] offset:192
	v_mov_b32_e32 v66, v208
	v_mov_b32_e32 v37, v167
	v_ashrrev_i32_e32 v14, 6, v66
	v_ashrrev_i32_e32 v15, 31, v14
	v_lshlrev_b64 v[14:15], 12, v[14:15]
	v_lshl_add_u64 v[14:15], v[14:15], 0, s[6:7]
	v_and_b32_e32 v70, 15, v66
	v_lshlrev_b64 v[14:15], 2, v[14:15]
	v_bfe_u32 v67, v66, 4, 2
	v_mov_b32_e32 v39, v167
	v_mov_b32_e32 v53, v167
	v_mov_b32_e32 v43, v167
	v_mov_b32_e32 v47, v167
	v_mov_b32_e32 v69, v167
	v_mov_b32_e32 v79, v167
	v_mov_b32_e32 v95, v167
	v_mov_b32_e32 v87, v167
	v_mov_b32_e32 v91, v167
	v_and_b32_e32 v73, 0xffffffc0, v66
	s_mov_b64 s[8:9], 0x74c2800
	s_waitcnt vmcnt(3)
	v_lshl_add_u64 v[4:5], v[4:5], 0, v[14:15]
	s_waitcnt vmcnt(2)
	v_lshl_add_u64 v[8:9], v[8:9], 0, v[14:15]
	v_lshlrev_b32_e32 v14, 2, v70
	v_lshl_or_b32 v166, v67, 11, v14
	v_or_b32_e32 v36, 0x2000, v166
	v_or_b32_e32 v38, 0x2100, v166
	v_or_b32_e32 v52, 0x2700, v166
	v_lshl_add_u64 v[16:17], v[8:9], 0, v[166:167]
	v_lshl_add_u64 v[14:15], v[4:5], 0, v[166:167]
	v_lshl_add_u64 v[34:35], v[8:9], 0, v[36:37]
	v_lshl_add_u64 v[40:41], v[8:9], 0, v[38:39]
	v_lshl_add_u64 v[50:51], v[8:9], 0, v[52:53]
	global_load_dword v18, v[16:17], off
	global_load_dword v19, v[16:17], off offset:256
	global_load_dword v20, v[14:15], off
	global_load_dword v21, v[14:15], off offset:256
	global_load_dword v22, v[16:17], off offset:512
	global_load_dword v23, v[16:17], off offset:768
	global_load_dword v24, v[14:15], off offset:512
	global_load_dword v26, v[14:15], off offset:768
	global_load_dword v27, v[16:17], off offset:1024
	global_load_dword v29, v[16:17], off offset:1280
	global_load_dword v30, v[14:15], off offset:1024
	global_load_dword v31, v[14:15], off offset:1280
	global_load_dword v32, v[16:17], off offset:1536
	global_load_dword v33, v[16:17], off offset:1792
	global_load_dword v25, v[14:15], off offset:1536
	global_load_dword v28, v[14:15], off offset:1792
	v_lshl_add_u64 v[36:37], v[4:5], 0, v[36:37]
	global_load_dword v34, v[34:35], off
	v_lshl_add_u64 v[38:39], v[4:5], 0, v[38:39]
	global_load_dword v35, v[40:41], off
	global_load_dword v60, v[50:51], off
	v_or_b32_e32 v40, 0x2200, v166
	v_mov_b32_e32 v41, v167
	v_or_b32_e32 v42, 0x2300, v166
	global_load_dword v36, v[36:37], off
	v_lshl_add_u64 v[44:45], v[8:9], 0, v[42:43]
	global_load_dword v37, v[38:39], off
	v_lshl_add_u64 v[38:39], v[8:9], 0, v[40:41]
	global_load_dword v38, v[38:39], off
	v_lshl_add_u64 v[40:41], v[4:5], 0, v[40:41]
	global_load_dword v39, v[44:45], off
	v_lshl_add_u64 v[42:43], v[4:5], 0, v[42:43]
	v_or_b32_e32 v44, 0x2400, v166
	v_mov_b32_e32 v45, v167
	v_or_b32_e32 v46, 0x2500, v166
	global_load_dword v40, v[40:41], off
	v_lshl_add_u64 v[48:49], v[8:9], 0, v[46:47]
	global_load_dword v41, v[42:43], off
	v_lshl_add_u64 v[42:43], v[8:9], 0, v[44:45]
	global_load_dword v42, v[42:43], off
	v_lshl_add_u64 v[44:45], v[4:5], 0, v[44:45]
	global_load_dword v43, v[48:49], off
	v_lshl_add_u64 v[46:47], v[4:5], 0, v[46:47]
	v_or_b32_e32 v48, 0x2600, v166
	v_mov_b32_e32 v49, v167
	global_load_dword v44, v[44:45], off
	v_or_b32_e32 v68, 0x2040, v166
	global_load_dword v45, v[46:47], off
	v_lshl_add_u64 v[46:47], v[8:9], 0, v[48:49]
	v_lshl_add_u64 v[48:49], v[4:5], 0, v[48:49]
	v_or_b32_e32 v78, 0x2140, v166
	v_or_b32_e32 v94, 0x2740, v166
	global_load_dword v50, v[48:49], off
	v_lshl_add_u64 v[48:49], v[4:5], 0, v[52:53]
	v_lshl_add_u64 v[74:75], v[8:9], 0, v[68:69]
	v_lshl_add_u64 v[76:77], v[8:9], 0, v[78:79]
	v_lshl_add_u64 v[68:69], v[4:5], 0, v[68:69]
	v_lshl_add_u64 v[92:93], v[8:9], 0, v[94:95]
	global_load_dword v46, v[46:47], off
	s_nop 0
	global_load_dword v56, v[48:49], off
	global_load_dword v47, v[16:17], off offset:64
	s_nop 0
	global_load_dword v48, v[16:17], off offset:320
	global_load_dword v49, v[14:15], off offset:64
	global_load_dword v51, v[14:15], off offset:320
	global_load_dword v52, v[16:17], off offset:576
	global_load_dword v53, v[16:17], off offset:832
	global_load_dword v54, v[14:15], off offset:576
	global_load_dword v57, v[14:15], off offset:832
	global_load_dword v58, v[16:17], off offset:1088
	global_load_dword v61, v[16:17], off offset:1344
	global_load_dword v62, v[14:15], off offset:1088
	global_load_dword v63, v[14:15], off offset:1344
	global_load_dword v71, v[16:17], off offset:1600
	global_load_dword v72, v[16:17], off offset:1856
	global_load_dword v55, v[14:15], off offset:1600
	global_load_dword v59, v[14:15], off offset:1856
	v_or_b32_e32 v86, 0x2340, v166
	global_load_dword v74, v[74:75], off
	v_lshl_add_u64 v[84:85], v[8:9], 0, v[86:87]
	global_load_dword v92, v[92:93], off
	v_or_b32_e32 v90, 0x2540, v166
	global_load_dword v75, v[76:77], off
	v_lshl_add_u64 v[88:89], v[8:9], 0, v[90:91]
	global_load_dword v76, v[68:69], off
	v_lshl_add_u64 v[68:69], v[4:5], 0, v[78:79]
	global_load_dword v77, v[68:69], off
	v_or_b32_e32 v68, 0x2240, v166
	v_mov_b32_e32 v69, v167
	v_lshl_add_u64 v[78:79], v[8:9], 0, v[68:69]
	v_lshl_add_u64 v[68:69], v[4:5], 0, v[68:69]
	global_load_dword v78, v[78:79], off
	s_waitcnt vmcnt(54)
	v_lshl_add_u64 v[100:101], v[64:65], 0, s[8:9]
	global_load_dword v79, v[84:85], off
	s_mul_i32 s9, s83, 0xfffffa00
	global_load_dword v84, v[68:69], off
	v_lshl_add_u64 v[68:69], v[4:5], 0, v[86:87]
	global_load_dword v85, v[68:69], off
	v_or_b32_e32 v68, 0x2440, v166
	v_mov_b32_e32 v69, v167
	v_lshl_add_u64 v[86:87], v[8:9], 0, v[68:69]
	v_lshl_add_u64 v[68:69], v[4:5], 0, v[68:69]
	global_load_dword v86, v[86:87], off
	s_lshl_b32 s8, s15, 6
	global_load_dword v87, v[88:89], off
	s_nop 0
	global_load_dword v88, v[68:69], off
	v_lshl_add_u64 v[68:69], v[4:5], 0, v[90:91]
	global_load_dword v89, v[68:69], off
	v_or_b32_e32 v68, 0x2640, v166
	v_mov_b32_e32 v69, v167
	v_lshl_add_u64 v[90:91], v[8:9], 0, v[68:69]
	v_lshl_add_u64 v[68:69], v[4:5], 0, v[68:69]
	global_load_dword v90, v[90:91], off
	s_nop 0
	global_load_dword v91, v[68:69], off
	v_lshl_add_u64 v[68:69], v[4:5], 0, v[94:95]
	global_load_dword v105, v[68:69], off
	global_load_dword v93, v[16:17], off offset:128
	global_load_dword v94, v[16:17], off offset:384
	global_load_dword v95, v[14:15], off offset:128
	global_load_dword v96, v[14:15], off offset:384
	global_load_dword v97, v[16:17], off offset:640
	global_load_dword v98, v[16:17], off offset:896
	global_load_dword v99, v[14:15], off offset:640
	global_load_dword v106, v[14:15], off offset:896
	global_load_dword v107, v[16:17], off offset:1152
	global_load_dword v109, v[16:17], off offset:1408
	global_load_dword v110, v[14:15], off offset:1152
	global_load_dword v111, v[14:15], off offset:1408
	global_load_dword v112, v[16:17], off offset:1664
	global_load_dword v113, v[16:17], off offset:1920
	global_load_dword v104, v[14:15], off offset:1664
	global_load_dword v108, v[14:15], off offset:1920
	v_or_b32_e32 v68, 0x2080, v166
	v_mov_b32_e32 v69, v167
	v_lshl_add_u64 v[102:103], v[8:9], 0, v[68:69]
	global_load_dword v114, v[102:103], off
	v_or_b32_e32 v102, 0x2180, v166
	v_mov_b32_e32 v103, v167
	v_lshl_add_u64 v[116:117], v[8:9], 0, v[102:103]
	v_lshl_add_u64 v[68:69], v[4:5], 0, v[68:69]
	global_load_dword v116, v[116:117], off
	s_nop 0
	global_load_dword v117, v[68:69], off
	v_lshl_add_u64 v[68:69], v[4:5], 0, v[102:103]
	global_load_dword v118, v[68:69], off
	v_or_b32_e32 v68, 0x2280, v166
	v_mov_b32_e32 v69, v167
	v_lshl_add_u64 v[102:103], v[8:9], 0, v[68:69]
	global_load_dword v119, v[102:103], off
	v_or_b32_e32 v102, 0x2380, v166
	v_mov_b32_e32 v103, v167
	v_lshl_add_u64 v[120:121], v[8:9], 0, v[102:103]
	v_lshl_add_u64 v[68:69], v[4:5], 0, v[68:69]
	global_load_dword v120, v[120:121], off
	s_nop 0
	global_load_dword v121, v[68:69], off
	v_lshl_add_u64 v[68:69], v[4:5], 0, v[102:103]
	global_load_dword v122, v[68:69], off
	v_or_b32_e32 v68, 0x2480, v166
	v_mov_b32_e32 v69, v167
	v_lshl_add_u64 v[102:103], v[8:9], 0, v[68:69]
	global_load_dword v123, v[102:103], off
	v_or_b32_e32 v102, 0x2580, v166
	v_mov_b32_e32 v103, v167
	v_lshl_add_u64 v[124:125], v[8:9], 0, v[102:103]
	v_lshl_add_u64 v[68:69], v[4:5], 0, v[68:69]
	global_load_dword v124, v[124:125], off
	s_nop 0
	global_load_dword v125, v[68:69], off
	v_lshl_add_u64 v[68:69], v[4:5], 0, v[102:103]
	global_load_dword v140, v[68:69], off
	v_or_b32_e32 v68, 0x2680, v166
	v_mov_b32_e32 v69, v167
	v_lshl_add_u64 v[102:103], v[8:9], 0, v[68:69]
	global_load_dword v141, v[102:103], off
	v_or_b32_e32 v102, 0x2780, v166
	v_mov_b32_e32 v103, v167
	v_lshl_add_u64 v[68:69], v[4:5], 0, v[68:69]
	v_lshl_add_u64 v[126:127], v[8:9], 0, v[102:103]
	global_load_dword v142, v[68:69], off
	v_lshl_add_u64 v[68:69], v[4:5], 0, v[102:103]
	global_load_dword v143, v[126:127], off
	global_load_dword v145, v[68:69], off
	global_load_dword v144, v[16:17], off offset:192
	global_load_dword v146, v[16:17], off offset:448
	global_load_dword v147, v[14:15], off offset:192
	global_load_dword v149, v[14:15], off offset:448
	global_load_dword v150, v[16:17], off offset:704
	global_load_dword v151, v[16:17], off offset:960
	global_load_dword v152, v[14:15], off offset:704
	global_load_dword v153, v[14:15], off offset:960
	global_load_dword v154, v[16:17], off offset:1216
	global_load_dword v155, v[16:17], off offset:1472
	global_load_dword v156, v[14:15], off offset:1216
	global_load_dword v157, v[14:15], off offset:1472
	global_load_dword v158, v[16:17], off offset:1728
	global_load_dword v161, v[16:17], off offset:1984
	global_load_dword v160, v[14:15], off offset:1728
	global_load_dword v162, v[14:15], off offset:1984
	v_or_b32_e32 v14, 0x20c0, v166
	v_mov_b32_e32 v15, v167
	v_lshl_add_u64 v[16:17], v[8:9], 0, v[14:15]
	global_load_dword v163, v[16:17], off
	v_or_b32_e32 v16, 0x21c0, v166
	v_mov_b32_e32 v17, v167
	v_lshl_add_u64 v[14:15], v[4:5], 0, v[14:15]
	global_load_dword v165, v[14:15], off
	v_lshl_add_u64 v[14:15], v[4:5], 0, v[16:17]
	global_load_dword v169, v[14:15], off
	v_or_b32_e32 v14, 0x22c0, v166
	v_mov_b32_e32 v15, v167
	v_lshl_add_u64 v[68:69], v[8:9], 0, v[16:17]
	v_lshl_add_u64 v[16:17], v[8:9], 0, v[14:15]
	global_load_dword v164, v[68:69], off
	global_load_dword v176, v[16:17], off
	v_or_b32_e32 v16, 0x23c0, v166
	v_mov_b32_e32 v17, v167
	v_lshl_add_u64 v[14:15], v[4:5], 0, v[14:15]
	global_load_dword v178, v[14:15], off
	v_lshl_add_u64 v[14:15], v[4:5], 0, v[16:17]
	global_load_dword v180, v[14:15], off
	v_or_b32_e32 v14, 0x24c0, v166
	v_mov_b32_e32 v15, v167
	v_lshl_add_u64 v[68:69], v[8:9], 0, v[16:17]
	v_lshl_add_u64 v[16:17], v[8:9], 0, v[14:15]
	global_load_dword v177, v[68:69], off
	global_load_dword v182, v[16:17], off
	v_or_b32_e32 v16, 0x25c0, v166
	v_mov_b32_e32 v17, v167
	v_lshl_add_u64 v[14:15], v[4:5], 0, v[14:15]
	global_load_dword v179, v[14:15], off
	v_lshl_add_u64 v[14:15], v[4:5], 0, v[16:17]
	global_load_dword v181, v[14:15], off
	v_or_b32_e32 v14, 0x26c0, v166
	v_mov_b32_e32 v15, v167
	v_or_b32_e32 v166, 0x27c0, v166
	v_lshl_add_u64 v[68:69], v[8:9], 0, v[16:17]
	v_lshl_add_u64 v[16:17], v[8:9], 0, v[14:15]
	v_lshl_add_u64 v[8:9], v[8:9], 0, v[166:167]
	global_load_dword v184, v[68:69], off
	global_load_dword v183, v[16:17], off
	global_load_dword v185, v[8:9], off
	v_lshl_add_u64 v[8:9], v[4:5], 0, v[14:15]
	v_lshl_add_u64 v[4:5], v[4:5], 0, v[166:167]
	global_load_dword v186, v[8:9], off
	global_load_dword v187, v[4:5], off
	v_add_u32_e32 v4, s37, v73
	v_or_b32_e32 v4, v4, v70
	v_ashrrev_i32_e32 v5, 31, v4
	v_lshlrev_b64 v[4:5], 2, v[4:5]
	v_lshl_add_u64 v[8:9], v[10:11], 0, v[4:5]
	v_lshl_add_u64 v[6:7], v[6:7], 0, v[4:5]
	v_lshl_add_u64 v[4:5], v[12:13], 0, v[4:5]
	global_load_dword v126, v[8:9], off
	global_load_dword v127, v[6:7], off
	global_load_dword v188, v[4:5], off
	global_load_dword v128, v[8:9], off offset:64
	global_load_dword v129, v[6:7], off offset:64
	global_load_dword v159, v[4:5], off offset:64
	global_load_dword v130, v[8:9], off offset:128
	global_load_dword v131, v[6:7], off offset:128
	global_load_dword v148, v[4:5], off offset:128
	global_load_dword v132, v[8:9], off offset:192
	global_load_dword v133, v[6:7], off offset:192
	global_load_dword v115, v[4:5], off offset:192
	v_add_u32_e32 v4, s5, v66
	v_ashrrev_i32_e32 v5, 31, v4
	v_lshl_add_u64 v[6:7], v[4:5], 2, v[0:1]
	global_load_dword v134, v[6:7], off
	global_load_dword v135, v[6:7], off offset:2048
	v_add_u32_e32 v6, s12, v66
	v_ashrrev_i32_e32 v7, 31, v6
	v_lshl_add_u64 v[6:7], v[6:7], 2, v[0:1]
	global_load_dword v136, v[6:7], off
	v_add_u32_e32 v6, s13, v66
	v_ashrrev_i32_e32 v7, 31, v6
	v_lshl_add_u64 v[0:1], v[6:7], 2, v[0:1]
	global_load_dword v137, v[0:1], off
	v_add_u32_e32 v0, s9, v4
	v_ashrrev_i32_e32 v1, 31, v0
	v_lshl_add_u64 v[0:1], v[0:1], 2, v[2:3]
	global_load_dword v138, v[0:1], off
	s_and_b32 s9, s15, 31
	v_add_u32_e32 v0, 0xa00, v66
	s_cmp_lg_u32 s9, 0
	v_and_b32_e32 v166, 0xff, v66
	v_ashrrev_i32_e32 v102, 8, v0
	s_cbranch_scc0 .LBB0_321
	s_add_i32 s10, s8, -3
	s_ashr_i32 s11, s10, 31
	s_lshr_b64 s[16:17], s[10:11], 8
	v_ashrrev_i32_e32 v103, 31, v102
	v_mad_u64_u32 v[0:1], s[16:17], s16, 49, v[102:103]
	v_mov_b32_e32 v2, v1
	s_lshr_b32 s9, s11, 8
	v_mad_u64_u32 v[2:3], s[16:17], s9, 49, v[2:3]
	v_mov_b32_e32 v1, v2
	v_lshlrev_b64 v[0:1], 17, v[0:1]
	s_lshl_b32 s9, s10, 9
	v_lshl_add_u64 v[0:1], v[100:101], 0, v[0:1]
	s_and_b32 s96, s9, 0x1fa00
	v_lshl_add_u64 v[0:1], v[0:1], 0, s[96:97]
	v_lshlrev_b32_e32 v2, 1, v166
	v_mov_b32_e32 v3, v167
	v_lshl_add_u64 v[0:1], v[0:1], 0, v[2:3]
	global_load_ushort v139, v[0:1], off
	s_add_i32 s10, s8, -2
	s_ashr_i32 s11, s10, 31
	s_lshr_b64 s[16:17], s[10:11], 8
	s_lshr_b32 s9, s11, 8
	v_mad_u64_u32 v[0:1], s[16:17], s16, 49, v[102:103]
	v_mov_b32_e32 v4, v1
	v_mad_u64_u32 v[4:5], s[16:17], s9, 49, v[4:5]
	s_lshl_b32 s9, s10, 9
	s_add_i32 s10, s8, -1
	s_ashr_i32 s11, s10, 31
	s_lshr_b64 s[16:17], s[10:11], 8
	v_mov_b32_e32 v1, v4
	v_mad_u64_u32 v[4:5], s[16:17], s16, 49, v[102:103]
	s_and_b32 s96, s9, 0x1fc00
	v_mov_b32_e32 v6, v5
	s_lshr_b32 s9, s11, 8
	v_mad_u64_u32 v[6:7], s[16:17], s9, 49, v[6:7]
	v_lshlrev_b64 v[0:1], 17, v[0:1]
	v_mov_b32_e32 v5, v6
	v_lshl_add_u64 v[0:1], v[100:101], 0, v[0:1]
	v_lshlrev_b64 v[4:5], 17, v[4:5]
	s_lshl_b32 s9, s10, 9
	v_lshl_add_u64 v[0:1], v[0:1], 0, s[96:97]
	v_lshl_add_u64 v[4:5], v[100:101], 0, v[4:5]
	s_and_b32 s96, s9, 0x1fe00
	v_lshl_add_u64 v[4:5], v[4:5], 0, s[96:97]
	v_lshl_add_u64 v[0:1], v[0:1], 0, v[2:3]
	v_lshl_add_u64 v[2:3], v[4:5], 0, v[2:3]
	global_load_ushort v68, v[2:3], off
	s_nop 0
	global_load_ushort v69, v[0:1], off
	s_cbranch_execnz .LBB0_314

.LBB0_314:
	s_waitcnt vmcnt(62)
	v_cvt_pk_bf16_f32 v1, v22, v23
	v_cvt_pk_bf16_f32 v23, v55, v59
	s_waitcnt vmcnt(14)
	v_mul_f32_e32 v59, 0xbfb8aa3b, v188
	v_cvt_pk_bf16_f32 v22, v62, v63
	v_rndne_f32_e32 v62, v59
	s_mov_b32 s2, 0xbfb8aa3b
	v_sub_f32_e32 v63, v59, v62
	v_fma_f32 v59, v188, s2, -v59
	v_fmac_f32_e32 v59, 0xb2a5705f, v188
	v_add_f32_e32 v59, v63, v59
	v_cvt_pk_bf16_f32 v0, v18, v19
	v_cvt_pk_bf16_f32 v19, v71, v72
	v_exp_f32_e32 v71, v59
	v_cvt_i32_f32_e32 v72, v62
	v_cmp_nlt_f32_e32 vcc, s3, v188
	v_cvt_pk_bf16_f32 v5, v24, v26
	v_cvt_pk_bf16_f32 v24, v74, v75
	v_ldexp_f32 v71, v71, v72
	v_cndmask_b32_e32 v71, 0, v71, vcc
	v_cmp_ngt_f32_e32 vcc, s20, v188
	v_cvt_pk_bf16_f32 v7, v25, v28
	v_cvt_pk_bf16_f32 v28, v76, v77
	v_cndmask_b32_e32 v71, v209, v71, vcc
	v_add_f32_e32 v72, 1.0, v71
	v_add_f32_e32 v74, -1.0, v72
	v_sub_f32_e32 v75, v74, v72
	v_add_f32_e32 v75, 1.0, v75
	v_sub_f32_e32 v74, v71, v74
	v_add_f32_e32 v76, v74, v75
	v_frexp_mant_f32_e32 v77, v72
	v_cvt_f64_f32_e32 v[74:75], v72
	s_mov_b32 s9, 0x3f2aaaab
	v_frexp_exp_i32_f64_e32 v74, v[74:75]
	v_cmp_gt_f32_e32 vcc, s9, v77
	v_cvt_pk_bf16_f32 v25, v78, v79
	v_cvt_pk_bf16_f32 v2, v27, v29
	v_subbrev_co_u32_e32 v74, vcc, 0, v74, vcc
	v_sub_u32_e32 v75, 0, v74
	v_ldexp_f32 v72, v72, v75
	v_ldexp_f32 v75, v76, v75
	v_add_f32_e32 v76, -1.0, v72
	v_add_f32_e32 v79, 1.0, v72
	v_cvt_pk_bf16_f32 v29, v84, v85
	v_add_f32_e32 v77, 1.0, v76
	v_add_f32_e32 v84, -1.0, v79
	v_sub_f32_e32 v77, v72, v77
	v_sub_f32_e32 v72, v72, v84
	v_add_f32_e32 v72, v75, v72
	v_add_f32_e32 v77, v75, v77
	v_add_f32_e32 v75, v79, v72
	v_rcp_f32_e32 v84, v75
	v_add_f32_e32 v78, v76, v77
	v_sub_f32_e32 v76, v76, v78
	v_add_f32_e32 v76, v77, v76
	v_sub_f32_e32 v77, v79, v75
	v_add_f32_e32 v72, v72, v77
	v_mul_f32_e32 v77, v78, v84
	v_mul_f32_e32 v79, v75, v77
	v_fma_f32 v85, v77, v75, -v79
	v_fmac_f32_e32 v85, v77, v72
	v_cvt_pk_bf16_f32 v26, v86, v87
	v_add_f32_e32 v86, v79, v85
	v_sub_f32_e32 v87, v78, v86
	v_sub_f32_e32 v78, v78, v87
	v_sub_f32_e32 v79, v86, v79
	v_sub_f32_e32 v78, v78, v86
	v_add_f32_e32 v76, v76, v78
	v_sub_f32_e32 v78, v79, v85
	v_add_f32_e32 v76, v78, v76
	v_add_f32_e32 v78, v87, v76
	v_mul_f32_e32 v79, v84, v78
	v_mul_f32_e32 v85, v75, v79
	v_fma_f32 v75, v79, v75, -v85
	v_fmac_f32_e32 v75, v79, v72
	v_sub_f32_e32 v72, v87, v78
	v_add_f32_e32 v72, v76, v72
	v_add_f32_e32 v76, v85, v75
	v_sub_f32_e32 v86, v78, v76
	v_sub_f32_e32 v78, v78, v86
	v_sub_f32_e32 v85, v76, v85
	v_sub_f32_e32 v76, v78, v76
	v_add_f32_e32 v72, v72, v76
	v_sub_f32_e32 v75, v85, v75
	v_cvt_f32_i32_e32 v74, v74
	v_add_f32_e32 v72, v75, v72
	v_add_f32_e32 v75, v77, v79
	v_add_f32_e32 v72, v86, v72
	v_sub_f32_e32 v76, v75, v77
	v_mul_f32_e32 v72, v84, v72
	v_sub_f32_e32 v76, v79, v76
	v_add_f32_e32 v72, v76, v72
	v_mul_f32_e32 v79, 0x3f317218, v74
	s_mov_b32 s18, 0x3f317218
	v_add_f32_e32 v76, v75, v72
	v_fma_f32 v84, v74, s18, -v79
	v_mul_f32_e32 v77, v76, v76
	v_fmac_f32_e32 v84, 0xb102e308, v74
	v_sub_f32_e32 v74, v76, v75
	v_fmamk_f32 v78, v77, 0x3e9b6dac, v217
	v_sub_f32_e32 v72, v72, v74
	v_add_f32_e32 v74, v79, v84
	v_fmaak_f32 v78, v77, v78, 0x3f2aaada
	v_sub_f32_e32 v75, v74, v79
	v_ldexp_f32 v79, v76, 1
	v_mul_f32_e32 v76, v76, v77
	v_mul_f32_e32 v76, v76, v78
	v_add_f32_e32 v77, v79, v76
	v_sub_f32_e32 v78, v77, v79
	v_ldexp_f32 v72, v72, 1
	v_sub_f32_e32 v76, v76, v78
	v_add_f32_e32 v72, v72, v76
	v_add_f32_e32 v76, v77, v72
	v_sub_f32_e32 v77, v76, v77
	v_sub_f32_e32 v72, v72, v77
	v_add_f32_e32 v77, v74, v76
	v_sub_f32_e32 v78, v77, v74
	v_sub_f32_e32 v79, v77, v78
	v_sub_f32_e32 v75, v84, v75
	v_sub_f32_e32 v74, v74, v79
	v_sub_f32_e32 v76, v76, v78
	v_add_f32_e32 v74, v76, v74
	v_add_f32_e32 v76, v75, v72
	v_sub_f32_e32 v78, v76, v75
	v_sub_f32_e32 v79, v76, v78
	v_sub_f32_e32 v75, v75, v79
	v_sub_f32_e32 v72, v72, v78
	v_add_f32_e32 v74, v76, v74
	v_add_f32_e32 v72, v72, v75
	v_add_f32_e32 v75, v77, v74
	v_sub_f32_e32 v76, v75, v77
	v_sub_f32_e32 v74, v74, v76
	v_add_f32_e32 v72, v72, v74
	s_waitcnt vmcnt(11)
	v_mul_f32_e32 v74, 0xbfb8aa3b, v159
	v_add_f32_e32 v72, v75, v72
	v_rndne_f32_e32 v75, v74
	v_sub_f32_e32 v76, v74, v75
	v_fma_f32 v74, v159, s2, -v74
	v_fmac_f32_e32 v74, 0xb2a5705f, v159
	v_add_f32_e32 v74, v76, v74
	s_mov_b32 s11, 0x7f800000
	v_exp_f32_e32 v74, v74
	v_cvt_i32_f32_e32 v75, v75
	v_cmp_neq_f32_e32 vcc, s11, v71
	s_mov_b32 s19, 0x33800000
	v_cvt_pk_bf16_f32 v11, v46, v60
	v_cndmask_b32_e32 v72, v209, v72, vcc
	v_cmp_lt_f32_e64 vcc, |v71|, s19
	v_cvt_pk_bf16_f32 v46, v125, v140
	v_cvt_pk_bf16_f32 v16, v47, v48
	v_cndmask_b32_e32 v71, v72, v71, vcc
	v_mul_f32_e32 v140, 0x41000000, v71
	v_ldexp_f32 v71, v74, v75
	v_cmp_nlt_f32_e32 vcc, s3, v159
	v_cvt_pk_bf16_f32 v47, v142, v145
	v_cvt_pk_bf16_f32 v10, v42, v43
	v_cndmask_b32_e32 v71, 0, v71, vcc
	v_cmp_ngt_f32_e32 vcc, s20, v159
	v_cvt_pk_bf16_f32 v43, v141, v143
	v_cvt_pk_bf16_f32 v6, v30, v31
	v_cndmask_b32_e32 v71, v209, v71, vcc
	v_add_f32_e32 v72, 1.0, v71
	v_add_f32_e32 v74, -1.0, v72
	v_sub_f32_e32 v75, v74, v72
	v_add_f32_e32 v75, 1.0, v75
	v_sub_f32_e32 v74, v71, v74
	v_add_f32_e32 v76, v74, v75
	v_frexp_mant_f32_e32 v77, v72
	v_cvt_f64_f32_e32 v[74:75], v72
	v_frexp_exp_i32_f64_e32 v74, v[74:75]
	v_cmp_gt_f32_e32 vcc, s9, v77
	v_cvt_pk_bf16_f32 v30, v88, v89
	v_cvt_pk_bf16_f32 v27, v90, v92
	v_subbrev_co_u32_e32 v74, vcc, 0, v74, vcc
	v_sub_u32_e32 v75, 0, v74
	v_ldexp_f32 v72, v72, v75
	v_ldexp_f32 v75, v76, v75
	v_add_f32_e32 v76, -1.0, v72
	v_add_f32_e32 v79, 1.0, v72
	v_add_f32_e32 v77, 1.0, v76
	v_add_f32_e32 v84, -1.0, v79
	v_sub_f32_e32 v77, v72, v77
	v_sub_f32_e32 v72, v72, v84
	v_add_f32_e32 v72, v75, v72
	v_add_f32_e32 v77, v75, v77
	v_add_f32_e32 v75, v79, v72
	v_rcp_f32_e32 v84, v75
	v_add_f32_e32 v78, v76, v77
	v_sub_f32_e32 v76, v76, v78
	v_add_f32_e32 v76, v77, v76
	v_sub_f32_e32 v77, v79, v75
	v_add_f32_e32 v72, v72, v77
	v_mul_f32_e32 v77, v78, v84
	v_mul_f32_e32 v79, v75, v77
	v_fma_f32 v85, v77, v75, -v79
	v_fmac_f32_e32 v85, v77, v72
	v_add_f32_e32 v86, v79, v85
	v_sub_f32_e32 v87, v78, v86
	v_sub_f32_e32 v78, v78, v87
	v_sub_f32_e32 v79, v86, v79
	v_sub_f32_e32 v78, v78, v86
	v_add_f32_e32 v76, v76, v78
	v_sub_f32_e32 v78, v79, v85
	v_add_f32_e32 v76, v78, v76
	v_add_f32_e32 v78, v87, v76
	v_mul_f32_e32 v79, v84, v78
	v_mul_f32_e32 v85, v75, v79
	v_fma_f32 v75, v79, v75, -v85
	v_fmac_f32_e32 v75, v79, v72
	v_sub_f32_e32 v72, v87, v78
	v_add_f32_e32 v72, v76, v72
	v_add_f32_e32 v76, v85, v75
	v_sub_f32_e32 v86, v78, v76
	v_sub_f32_e32 v78, v78, v86
	v_sub_f32_e32 v85, v76, v85
	v_sub_f32_e32 v76, v78, v76
	v_add_f32_e32 v72, v72, v76
	v_sub_f32_e32 v75, v85, v75
	v_cvt_f32_i32_e32 v74, v74
	v_add_f32_e32 v72, v75, v72
	v_add_f32_e32 v75, v77, v79
	v_add_f32_e32 v72, v86, v72
	v_sub_f32_e32 v76, v75, v77
	v_mul_f32_e32 v72, v84, v72
	v_sub_f32_e32 v76, v79, v76
	v_add_f32_e32 v72, v76, v72
	v_mul_f32_e32 v79, 0x3f317218, v74
	v_add_f32_e32 v76, v75, v72
	v_fma_f32 v84, v74, s18, -v79
	v_mul_f32_e32 v77, v76, v76
	v_fmac_f32_e32 v84, 0xb102e308, v74
	v_sub_f32_e32 v74, v76, v75
	v_fmamk_f32 v78, v77, 0x3e9b6dac, v217
	v_sub_f32_e32 v72, v72, v74
	v_add_f32_e32 v74, v79, v84
	v_fmaak_f32 v78, v77, v78, 0x3f2aaada
	v_sub_f32_e32 v75, v74, v79
	v_ldexp_f32 v79, v76, 1
	v_mul_f32_e32 v76, v76, v77
	v_mul_f32_e32 v76, v76, v78
	v_add_f32_e32 v77, v79, v76
	v_sub_f32_e32 v78, v77, v79
	v_ldexp_f32 v72, v72, 1
	v_sub_f32_e32 v76, v76, v78
	v_add_f32_e32 v72, v72, v76
	v_add_f32_e32 v76, v77, v72
	v_sub_f32_e32 v77, v76, v77
	v_sub_f32_e32 v72, v72, v77
	v_add_f32_e32 v77, v74, v76
	v_sub_f32_e32 v78, v77, v74
	v_sub_f32_e32 v79, v77, v78
	v_sub_f32_e32 v75, v84, v75
	v_sub_f32_e32 v74, v74, v79
	v_sub_f32_e32 v76, v76, v78
	v_add_f32_e32 v74, v76, v74
	v_add_f32_e32 v76, v75, v72
	v_sub_f32_e32 v78, v76, v75
	v_sub_f32_e32 v79, v76, v78
	v_sub_f32_e32 v75, v75, v79
	v_sub_f32_e32 v72, v72, v78
	v_add_f32_e32 v74, v76, v74
	v_add_f32_e32 v72, v72, v75
	v_add_f32_e32 v75, v77, v74
	v_sub_f32_e32 v76, v75, v77
	v_sub_f32_e32 v74, v74, v76
	v_add_f32_e32 v72, v72, v74
	s_waitcnt vmcnt(8)
	v_mul_f32_e32 v74, 0xbfb8aa3b, v148
	v_add_f32_e32 v72, v75, v72
	v_rndne_f32_e32 v75, v74
	v_sub_f32_e32 v76, v74, v75
	v_fma_f32 v74, v148, s2, -v74
	v_fmac_f32_e32 v74, 0xb2a5705f, v148
	v_add_f32_e32 v74, v76, v74
	v_exp_f32_e32 v74, v74
	v_cvt_i32_f32_e32 v75, v75
	v_cmp_neq_f32_e32 vcc, s11, v71
	v_cvt_pk_bf16_f32 v31, v91, v105
	v_cvt_pk_bf16_f32 v3, v32, v33
	v_cndmask_b32_e32 v72, v209, v72, vcc
	v_cmp_lt_f32_e64 vcc, |v71|, s19
	v_cvt_pk_bf16_f32 v12, v36, v37
	v_cvt_pk_bf16_f32 v32, v93, v94
	v_cndmask_b32_e32 v71, v72, v71, vcc
	v_mul_f32_e32 v142, 0x41000000, v71
	v_ldexp_f32 v71, v74, v75
	v_cmp_nlt_f32_e32 vcc, s3, v148
	v_cvt_pk_bf16_f32 v36, v95, v96
	v_cvt_pk_bf16_f32 v8, v34, v35
	v_cndmask_b32_e32 v71, 0, v71, vcc
	v_cmp_ngt_f32_e32 vcc, s20, v148
	v_cvt_pk_bf16_f32 v9, v38, v39
	v_cvt_pk_bf16_f32 v33, v97, v98
	v_cndmask_b32_e32 v71, v209, v71, vcc
	v_add_f32_e32 v72, 1.0, v71
	v_add_f32_e32 v74, -1.0, v72
	v_sub_f32_e32 v75, v74, v72
	v_add_f32_e32 v75, 1.0, v75
	v_sub_f32_e32 v74, v71, v74
	v_add_f32_e32 v76, v74, v75
	v_frexp_mant_f32_e32 v77, v72
	v_cvt_f64_f32_e32 v[74:75], v72
	v_frexp_exp_i32_f64_e32 v74, v[74:75]
	v_cmp_gt_f32_e32 vcc, s9, v77
	v_cvt_pk_bf16_f32 v37, v99, v106
	v_cvt_pk_bf16_f32 v34, v107, v109
	v_subbrev_co_u32_e32 v74, vcc, 0, v74, vcc
	v_sub_u32_e32 v75, 0, v74
	v_ldexp_f32 v72, v72, v75
	v_ldexp_f32 v75, v76, v75
	v_add_f32_e32 v76, -1.0, v72
	v_add_f32_e32 v79, 1.0, v72
	v_add_f32_e32 v77, 1.0, v76
	v_add_f32_e32 v84, -1.0, v79
	v_sub_f32_e32 v77, v72, v77
	v_sub_f32_e32 v72, v72, v84
	v_add_f32_e32 v72, v75, v72
	v_add_f32_e32 v77, v75, v77
	v_add_f32_e32 v75, v79, v72
	v_rcp_f32_e32 v84, v75
	v_add_f32_e32 v78, v76, v77
	v_sub_f32_e32 v76, v76, v78
	v_add_f32_e32 v76, v77, v76
	v_sub_f32_e32 v77, v79, v75
	v_add_f32_e32 v72, v72, v77
	v_mul_f32_e32 v77, v78, v84
	v_mul_f32_e32 v79, v75, v77
	v_fma_f32 v85, v77, v75, -v79
	v_fmac_f32_e32 v85, v77, v72
	v_add_f32_e32 v86, v79, v85
	v_sub_f32_e32 v87, v78, v86
	v_sub_f32_e32 v78, v78, v87
	v_sub_f32_e32 v79, v86, v79
	v_sub_f32_e32 v78, v78, v86
	v_add_f32_e32 v76, v76, v78
	v_sub_f32_e32 v78, v79, v85
	v_add_f32_e32 v76, v78, v76
	v_add_f32_e32 v78, v87, v76
	v_mul_f32_e32 v79, v84, v78
	v_mul_f32_e32 v85, v75, v79
	v_fma_f32 v75, v79, v75, -v85
	v_fmac_f32_e32 v75, v79, v72
	v_sub_f32_e32 v72, v87, v78
	v_add_f32_e32 v72, v76, v72
	v_add_f32_e32 v76, v85, v75
	v_sub_f32_e32 v86, v78, v76
	v_sub_f32_e32 v78, v78, v86
	v_sub_f32_e32 v85, v76, v85
	v_sub_f32_e32 v76, v78, v76
	v_add_f32_e32 v72, v72, v76
	v_sub_f32_e32 v75, v85, v75
	v_cvt_f32_i32_e32 v74, v74
	v_add_f32_e32 v72, v75, v72
	v_add_f32_e32 v75, v77, v79
	v_add_f32_e32 v72, v86, v72
	v_sub_f32_e32 v76, v75, v77
	v_mul_f32_e32 v72, v84, v72
	v_sub_f32_e32 v76, v79, v76
	v_add_f32_e32 v72, v76, v72
	v_mul_f32_e32 v79, 0x3f317218, v74
	v_add_f32_e32 v76, v75, v72
	v_fma_f32 v84, v74, s18, -v79
	v_mul_f32_e32 v77, v76, v76
	v_fmac_f32_e32 v84, 0xb102e308, v74
	v_sub_f32_e32 v74, v76, v75
	v_fmamk_f32 v78, v77, 0x3e9b6dac, v217
	v_sub_f32_e32 v72, v72, v74
	v_add_f32_e32 v74, v79, v84
	v_fmaak_f32 v78, v77, v78, 0x3f2aaada
	v_sub_f32_e32 v75, v74, v79
	v_ldexp_f32 v79, v76, 1
	v_mul_f32_e32 v76, v76, v77
	v_mul_f32_e32 v76, v76, v78
	v_add_f32_e32 v77, v79, v76
	v_sub_f32_e32 v78, v77, v79
	v_ldexp_f32 v72, v72, 1
	v_sub_f32_e32 v76, v76, v78
	v_add_f32_e32 v72, v72, v76
	v_add_f32_e32 v76, v77, v72
	v_sub_f32_e32 v77, v76, v77
	v_sub_f32_e32 v72, v72, v77
	v_add_f32_e32 v77, v74, v76
	v_sub_f32_e32 v78, v77, v74
	v_sub_f32_e32 v79, v77, v78
	v_sub_f32_e32 v75, v84, v75
	v_sub_f32_e32 v74, v74, v79
	v_sub_f32_e32 v76, v76, v78
	v_add_f32_e32 v74, v76, v74
	v_add_f32_e32 v76, v75, v72
	v_sub_f32_e32 v78, v76, v75
	v_sub_f32_e32 v79, v76, v78
	v_sub_f32_e32 v75, v75, v79
	v_sub_f32_e32 v72, v72, v78
	v_add_f32_e32 v74, v76, v74
	v_add_f32_e32 v72, v72, v75
	v_add_f32_e32 v75, v77, v74
	v_sub_f32_e32 v76, v75, v77
	v_sub_f32_e32 v74, v74, v76
	v_add_f32_e32 v72, v72, v74
	s_waitcnt vmcnt(5)
	v_mul_f32_e32 v74, 0xbfb8aa3b, v115
	v_add_f32_e32 v72, v75, v72
	v_rndne_f32_e32 v75, v74
	v_sub_f32_e32 v76, v74, v75
	v_fma_f32 v74, v115, s2, -v74
	v_fmac_f32_e32 v74, 0xb2a5705f, v115
	v_add_f32_e32 v74, v76, v74
	v_exp_f32_e32 v74, v74
	v_cvt_i32_f32_e32 v75, v75
	v_cmp_neq_f32_e32 vcc, s11, v71
	v_cvt_pk_bf16_f32 v39, v104, v108
	v_mul_u32_u24_e32 v70, 0x410, v70
	v_cndmask_b32_e32 v72, v209, v72, vcc
	v_cmp_lt_f32_e64 vcc, |v71|, s19
	v_cvt_pk_bf16_f32 v14, v44, v45
	v_cvt_pk_bf16_f32 v44, v117, v118
	v_cndmask_b32_e32 v71, v72, v71, vcc
	v_mul_f32_e32 v143, 0x41000000, v71
	v_ldexp_f32 v71, v74, v75
	v_cmp_nlt_f32_e32 vcc, s3, v115
	v_cvt_pk_bf16_f32 v45, v121, v122
	v_cvt_pk_bf16_f32 v42, v123, v124
	v_cndmask_b32_e32 v71, 0, v71, vcc
	v_cmp_ngt_f32_e32 vcc, s20, v115
	v_cvt_pk_bf16_f32 v48, v144, v146
	v_cvt_pk_bf16_f32 v17, v52, v53
	v_cndmask_b32_e32 v71, v209, v71, vcc
	v_add_f32_e32 v72, 1.0, v71
	v_add_f32_e32 v74, -1.0, v72
	v_sub_f32_e32 v75, v74, v72
	v_add_f32_e32 v75, 1.0, v75
	v_sub_f32_e32 v74, v71, v74
	v_add_f32_e32 v76, v74, v75
	v_frexp_mant_f32_e32 v77, v72
	v_cvt_f64_f32_e32 v[74:75], v72
	v_frexp_exp_i32_f64_e32 v74, v[74:75]
	v_cmp_gt_f32_e32 vcc, s9, v77
	s_ashr_i32 s9, s8, 31
	s_lshr_b64 s[16:17], s[8:9], 8
	v_subbrev_co_u32_e32 v78, vcc, 0, v74, vcc
	v_sub_u32_e32 v74, 0, v78
	v_ldexp_f32 v72, v72, v74
	v_add_f32_e32 v75, -1.0, v72
	v_add_f32_e32 v79, 1.0, v72
	v_ldexp_f32 v74, v76, v74
	v_add_f32_e32 v76, 1.0, v75
	v_add_f32_e32 v84, -1.0, v79
	v_sub_f32_e32 v76, v72, v76
	v_sub_f32_e32 v72, v72, v84
	v_add_f32_e32 v72, v74, v72
	v_add_f32_e32 v84, v79, v72
	v_rcp_f32_e32 v85, v84
	v_add_f32_e32 v76, v74, v76
	v_add_f32_e32 v77, v75, v76
	v_sub_f32_e32 v74, v79, v84
	v_mul_f32_e32 v87, v77, v85
	v_add_f32_e32 v79, v72, v74
	v_mul_f32_e32 v72, v84, v87
	v_fma_f32 v88, v87, v84, -v72
	v_fmac_f32_e32 v88, v87, v79
	v_add_f32_e32 v74, v72, v88
	v_sub_f32_e32 v90, v77, v74
	v_sub_f32_e32 v75, v75, v77
	v_sub_f32_e32 v89, v74, v72
	v_sub_f32_e32 v72, v77, v90
	v_add_f32_e32 v86, v76, v75
	v_sub_f32_e32 v91, v72, v74
	v_mad_u64_u32 v[74:75], s[16:17], s16, 49, v[102:103]
	s_lshr_b32 s9, s9, 8
	v_mov_b32_e32 v72, v75
	v_mad_u64_u32 v[76:77], s[16:17], s9, 49, v[72:73]
	v_mov_b32_e32 v75, v76
	v_lshlrev_b64 v[74:75], 17, v[74:75]
	s_lshl_b32 s9, s8, 9
	v_lshl_add_u64 v[74:75], v[100:101], 0, v[74:75]
	s_and_b32 s96, s9, 0x18000
	v_lshl_add_u64 v[74:75], v[74:75], 0, s[96:97]
	v_lshl_add_u64 v[74:75], v[166:167], 1, v[74:75]
	global_load_ushort v72, v[74:75], off offset:512
	global_load_ushort v76, v[74:75], off offset:1536
	global_load_ushort v77, v[74:75], off offset:2560
	global_load_ushort v92, v[74:75], off offset:3584
	global_load_ushort v93, v[74:75], off offset:3072
	global_load_ushort v94, v[74:75], off offset:2048
	global_load_ushort v95, v[74:75], off offset:1024
	global_load_ushort v96, v[74:75], off
	v_add_co_u32_e32 v74, vcc, s91, v74
	v_cvt_f32_i32_e32 v78, v78
	s_nop 0
	v_addc_co_u32_e32 v75, vcc, 0, v75, vcc
	global_load_ushort v97, v[74:75], off offset:512
	global_load_ushort v98, v[74:75], off offset:1536
	global_load_ushort v99, v[74:75], off offset:2560
	global_load_ushort v104, v[74:75], off offset:3584
	global_load_ushort v105, v[74:75], off offset:3072
	global_load_ushort v106, v[74:75], off offset:2048
	global_load_ushort v107, v[74:75], off offset:1024
	s_nop 0
	global_load_ushort v74, v[74:75], off
	v_add_f32_e32 v75, v86, v91
	v_sub_f32_e32 v86, v89, v88
	v_add_f32_e32 v75, v86, v75
	v_add_f32_e32 v86, v90, v75
	v_mul_f32_e32 v88, v85, v86
	v_mul_f32_e32 v89, v84, v88
	v_fma_f32 v84, v88, v84, -v89
	v_fmac_f32_e32 v84, v88, v79
	v_sub_f32_e32 v79, v90, v86
	v_add_f32_e32 v75, v75, v79
	v_add_f32_e32 v79, v89, v84
	v_sub_f32_e32 v90, v86, v79
	v_sub_f32_e32 v86, v86, v90
	v_sub_f32_e32 v89, v79, v89
	v_sub_f32_e32 v79, v86, v79
	v_add_f32_e32 v75, v75, v79
	v_sub_f32_e32 v79, v89, v84
	v_add_f32_e32 v75, v79, v75
	v_add_f32_e32 v79, v87, v88
	v_add_f32_e32 v75, v90, v75
	v_sub_f32_e32 v84, v79, v87
	v_mul_f32_e32 v75, v85, v75
	v_sub_f32_e32 v84, v88, v84
	v_add_f32_e32 v75, v84, v75
	v_mul_f32_e32 v87, 0x3f317218, v78
	v_add_f32_e32 v84, v79, v75
	v_fma_f32 v88, v78, s18, -v87
	v_mul_f32_e32 v85, v84, v84
	v_fmac_f32_e32 v88, 0xb102e308, v78
	v_sub_f32_e32 v78, v84, v79
	v_fmamk_f32 v86, v85, 0x3e9b6dac, v217
	v_sub_f32_e32 v75, v75, v78
	v_add_f32_e32 v78, v87, v88
	v_fmaak_f32 v86, v85, v86, 0x3f2aaada
	v_sub_f32_e32 v79, v78, v87
	v_ldexp_f32 v87, v84, 1
	v_mul_f32_e32 v84, v84, v85
	v_mul_f32_e32 v84, v84, v86
	v_add_f32_e32 v85, v87, v84
	v_sub_f32_e32 v86, v85, v87
	v_ldexp_f32 v75, v75, 1
	v_sub_f32_e32 v84, v84, v86
	v_add_f32_e32 v75, v75, v84
	v_add_f32_e32 v84, v85, v75
	v_sub_f32_e32 v85, v84, v85
	v_sub_f32_e32 v75, v75, v85
	v_add_f32_e32 v85, v78, v84
	v_sub_f32_e32 v86, v85, v78
	v_sub_f32_e32 v87, v85, v86
	v_sub_f32_e32 v79, v88, v79
	v_sub_f32_e32 v78, v78, v87
	v_sub_f32_e32 v84, v84, v86
	v_add_f32_e32 v78, v84, v78
	v_add_f32_e32 v84, v79, v75
	v_sub_f32_e32 v86, v84, v79
	v_sub_f32_e32 v87, v84, v86
	v_sub_f32_e32 v79, v79, v87
	v_sub_f32_e32 v75, v75, v86
	v_add_f32_e32 v78, v84, v78
	v_add_f32_e32 v75, v75, v79
	v_add_f32_e32 v79, v85, v78
	v_sub_f32_e32 v84, v79, v85
	v_sub_f32_e32 v78, v78, v84
	v_add_f32_e32 v75, v75, v78
	v_add_f32_e32 v75, v79, v75
	v_cmp_neq_f32_e32 vcc, s11, v71
	s_waitcnt vmcnt(15)
	v_lshlrev_b32_e32 v108, 16, v72
	v_lshlrev_b32_e32 v72, 1, v73
	v_cndmask_b32_e32 v75, v209, v75, vcc
	v_cmp_lt_f32_e64 vcc, |v71|, s19
	v_add3_u32 v70, 0, v70, v72
	v_lshlrev_b32_e32 v72, 4, v67
	v_lshlrev_b32_e32 v73, 11, v67
	v_ashrrev_i32_e32 v67, 31, v66
	v_cndmask_b32_e32 v71, v75, v71, vcc
	v_lshl_add_u64 v[64:65], v[66:67], 2, v[64:65]
	s_mov_b64 s[16:17], 0x2a4c2800
	v_mul_f32_e32 v144, 0x41000000, v71
	s_waitcnt vmcnt(3)
	v_lshlrev_b32_e32 v123, 16, v105
	s_waitcnt vmcnt(0)
	v_lshlrev_b32_e32 v139, 16, v139
	v_lshlrev_b32_e32 v68, 16, v68
	v_lshlrev_b32_e32 v69, 16, v69
	v_lshlrev_b32_e32 v117, 16, v74
	v_and_b32_e32 v74, 0x3fffffcf, v66
	v_lshlrev_b32_e32 v122, 16, v104
	v_lshlrev_b32_e32 v71, 1, v66
	v_lshl_add_u64 v[104:105], v[64:65], 0, s[16:17]
	v_add_lshl_u32 v64, v73, v74, 2
	v_cvt_pk_bf16_f32 v52, v147, v149
	v_lshl_add_u32 v145, v66, 2, 0
	v_sub_u32_e32 v71, 0, v71
	v_add_u32_e32 v147, s21, v64
	v_cvt_pk_bf16_f32 v4, v20, v21
	v_cvt_pk_bf16_f32 v13, v40, v41
	v_cvt_pk_bf16_f32 v15, v50, v56
	v_cvt_pk_bf16_f32 v20, v49, v51
	v_cvt_pk_bf16_f32 v21, v54, v57
	v_cvt_pk_bf16_f32 v18, v58, v61
	v_cvt_pk_bf16_f32 v38, v110, v111
	v_cvt_pk_bf16_f32 v35, v112, v113
	v_cvt_pk_bf16_f32 v40, v114, v116
	v_cvt_pk_bf16_f32 v41, v119, v120
	v_cvt_pk_bf16_f32 v49, v150, v151
	v_cvt_pk_bf16_f32 v53, v152, v153
	v_cvt_pk_bf16_f32 v50, v154, v155
	v_cvt_pk_bf16_f32 v54, v156, v157
	v_cvt_pk_bf16_f32 v51, v158, v161
	v_cvt_pk_bf16_f32 v55, v160, v162
	v_cvt_pk_bf16_f32 v56, v163, v164
	v_cvt_pk_bf16_f32 v60, v165, v169
	v_cvt_pk_bf16_f32 v57, v176, v177
	v_cvt_pk_bf16_f32 v61, v178, v180
	v_cvt_pk_bf16_f32 v58, v182, v184
	v_cvt_pk_bf16_f32 v62, v179, v181
	v_cvt_pk_bf16_f32 v59, v183, v185
	v_cvt_pk_bf16_f32 v63, v186, v187
	v_mov_b32_e32 v141, 0
	s_mov_b32 s10, 0
	s_mov_b32 s56, 0x3f317218
	s_mov_b32 s55, 0x7f800000
	s_mov_b32 s57, 0x33800000
	v_lshlrev_b32_e32 v109, 16, v96
	v_lshlrev_b32_e32 v111, 16, v95
	v_lshlrev_b32_e32 v110, 16, v76
	v_lshlrev_b32_e32 v113, 16, v94
	v_lshlrev_b32_e32 v112, 16, v77
	v_lshlrev_b32_e32 v115, 16, v93
	v_lshlrev_b32_e32 v114, 16, v92
	v_lshlrev_b32_e32 v116, 16, v97
	v_lshlrev_b32_e32 v119, 16, v107
	v_lshlrev_b32_e32 v118, 16, v98
	v_lshlrev_b32_e32 v121, 16, v106
	v_lshlrev_b32_e32 v120, 16, v99
	s_or_b32 s11, s8, 16
	v_add_u32_e32 v146, 0, v64
	v_add_u32_e32 v148, 0x800, v147
	v_add_u32_e32 v149, 0x1000, v147
	v_add_u32_e32 v150, 0x1800, v147
	v_add_u32_e32 v151, 64, v147
	v_add_u32_e32 v152, 0x840, v147
	v_add_u32_e32 v153, 0x1040, v147
	v_add_u32_e32 v154, 0x1840, v147
	v_add_u32_e32 v155, 0x80, v147
	v_add_u32_e32 v156, 0x880, v147
	v_add_u32_e32 v157, 0x1080, v147
	v_add_u32_e32 v158, 0x1880, v147
	v_add_u32_e32 v159, 0xc0, v147
	v_add_u32_e32 v160, 0x8c0, v147
	v_add_u32_e32 v161, 0x10c0, v147
	v_add_u32_e32 v162, 0x18c0, v147
	v_mov_b32_e32 v165, 1.0
	v_add_u32_e32 v163, v145, v71
	v_add_u32_e32 v164, v70, v72

.LBB0_1302:
	s_or_b64 exec, exec, s[10:11]
	v_lshlrev_b32_e32 v0, 4, v39
	v_and_b32_e32 v0, 0xf0, v0
	v_ashrrev_i32_e32 v5, 4, v39
	v_add_u32_e32 v4, 0, v0
	v_lshlrev_b32_e32 v0, 7, v5
	v_ashrrev_i32_e32 v1, 31, v0
	v_and_b32_e32 v7, 15, v39
	v_lshlrev_b32_e32 v6, 4, v7
	v_lshlrev_b64 v[0:1], 1, v[0:1]
	v_or_b32_e32 v0, v0, v6
	s_waitcnt vmcnt(0)
	v_lshl_add_u64 v[0:1], v[16:17], 0, v[0:1]
	v_lshl_add_u64 v[0:1], v[0:1], 0, s[6:7]
	s_waitcnt lgkmcnt(0)
	s_barrier
	global_load_dwordx4 v[12:15], v[0:1], off
	v_mad_u64_u32 v[132:133], s[10:11], v5, s50, v[4:5]
	v_lshlrev_b32_e32 v11, 4, v20
	v_add_u32_e32 v0, 0x200, v39
	v_ashrrev_i32_e32 v5, 4, v0
	v_lshlrev_b32_e32 v0, 7, v5
	v_ashrrev_i32_e32 v1, 31, v0
	v_lshlrev_b64 v[0:1], 1, v[0:1]
	v_or_b32_e32 v0, v0, v6
	v_lshl_add_u64 v[0:1], v[16:17], 0, v[0:1]
	v_lshl_add_u64 v[0:1], v[0:1], 0, s[6:7]
	global_load_dwordx4 v[44:47], v[0:1], off
	v_mad_u64_u32 v[134:135], s[10:11], v5, s50, v[4:5]
	v_add_u32_e32 v0, 0x400, v39
	v_ashrrev_i32_e32 v5, 4, v0
	v_lshlrev_b32_e32 v0, 7, v5
	v_ashrrev_i32_e32 v1, 31, v0
	v_lshlrev_b64 v[0:1], 1, v[0:1]
	v_or_b32_e32 v0, v0, v6
	v_lshl_add_u64 v[0:1], v[16:17], 0, v[0:1]
	v_lshl_add_u64 v[0:1], v[0:1], 0, s[6:7]
	global_load_dwordx4 v[48:51], v[0:1], off
	v_mad_u64_u32 v[136:137], s[10:11], v5, s50, v[4:5]
	v_add_u32_e32 v0, 0x600, v39
	v_ashrrev_i32_e32 v5, 4, v0
	v_lshlrev_b32_e32 v0, 7, v5
	v_ashrrev_i32_e32 v1, 31, v0
	v_lshlrev_b64 v[0:1], 1, v[0:1]
	v_or_b32_e32 v0, v0, v6
	v_lshl_add_u64 v[0:1], v[16:17], 0, v[0:1]
	v_lshl_add_u64 v[0:1], v[0:1], 0, s[6:7]
	global_load_dwordx4 v[52:55], v[0:1], off
	v_mad_u64_u32 v[4:5], s[10:11], v5, s50, v[4:5]
	v_mov_b32_e32 v5, 0
	s_waitcnt vmcnt(0)
	ds_write_b128 v132, v[12:15]
	ds_write_b128 v134, v[44:47]
	ds_write_b128 v136, v[48:51]
	ds_write_b128 v4, v[52:55]
	v_lshlrev_b32_e32 v0, 1, v35
	v_and_b32_e32 v1, 2, v0
	v_mad_u64_u32 v[2:3], s[10:11], v20, v20, v[20:21]
	v_or_b32_e32 v0, v11, v7
	v_mul_lo_u32 v0, v0, s50
	v_and_b32_e32 v3, 48, v40
	v_add3_u32 v8, 0, v0, v3
	v_lshl_add_u32 v9, v2, 3, v7
	v_add_u32_e32 v6, s2, v3
	v_cmp_gt_i32_e32 vcc, v1, v20
	v_cmp_le_i32_e64 s[10:11], v1, v20
	v_lshlrev_b32_e32 v10, 4, v1
	v_mov_b32_e32 v0, 0
	v_mov_b32_e32 v2, 0
	v_mov_b32_e32 v3, 0
	v_mov_b32_e32 v4, 0
	s_and_saveexec_b64 s[12:13], s[10:11]
	s_cbranch_execz .LBB0_1304
	v_add_u32_e32 v2, v9, v10
	v_mad_u64_u32 v[46:47], s[10:11], v2, s50, v[6:7]
	ds_read_b128 v[2:5], v8 offset:34816
	ds_read_b128 v[12:15], v46
	s_waitcnt lgkmcnt(0)
	v_mfma_f32_16x16x32_bf16 v[2:5], v[2:5], v[12:15], 0
	ds_read_b128 v[12:15], v8 offset:34880
	ds_read_b128 v[42:45], v46 offset:64
	s_waitcnt lgkmcnt(0)
	v_mfma_f32_16x16x32_bf16 v[2:5], v[12:15], v[42:45], v[2:5]
	ds_read_b128 v[12:15], v8 offset:34944
	ds_read_b128 v[42:45], v46 offset:128
	s_waitcnt lgkmcnt(0)
	v_mfma_f32_16x16x32_bf16 v[2:5], v[12:15], v[42:45], v[2:5]
	ds_read_b128 v[12:15], v8 offset:35008
	ds_read_b128 v[42:45], v46 offset:192
	s_waitcnt lgkmcnt(0)
	v_mfma_f32_16x16x32_bf16 v[2:5], v[12:15], v[42:45], v[2:5]
